# nt on the write-once sparse-attention output stores (keep the latent/key working set in L2)
# baseline (speedup 1.0000x reference)
; __device__ __forceinline__ unsigned cvt_pk_bf16(float lo, float hi) { unsigned r; asm volatile("v_cvt_pk_bf16_f32 %0, %1, %2" : "=v"(r) : "v"(lo), "v"(hi)); return r; }
; __device__ __forceinline__ void attn_item(const Ptrs& P, unsigned char* lds, int b, int tq0, int tid) {
;     ...
;         if (lane == 0) xa[48 + w] = aseq;
;         while (xa[48 + (w ^ 1)] != aseq) { }
;         const float* pc = (const float*)(stg + (w ^ 1) * 32 * SP);
;         float wa[4], wb[4];
; #pragma unroll
;         for (int j = 0; j < 4; ++j) { const float mo = pc[2048 + j * 64 + lane], lo = pc[2304 + j * 64 + lane];
;             const float mm = fmaxf(mrun[j], mo); const float ea = __expf(mrun[j] - mm), eb = __expf(mo - mm);
;             const float inv = 1.f / (lrun[j] * ea + lo * eb); wa[j] = ea * inv; wb[j] = eb * inv; }
;         bf16_t* op = P.QL + (rowb + tq) * 4096;
; #pragma unroll
;         for (int dt = 0; dt < 8; ++dt)
; #pragma unroll
;             for (int j = 0; j < 4; ++j) { const float v = (half ? oacc[8 + dt][j] : oacc[dt][j]) * wa[j] + pc[(dt * 4 + j) * 64 + lane] * wb[j];
;                 op[(4 * g + j) * 256 + 16 * (8 * half + dt) + r16] = (bf16_t)(cvt_pk_bf16(v, 0.f) & 0xffffu); }
.LBB0_931:
	v_mov_b64_e32 v[0:1], s[20:21]
	ds_read_b32 v0, v0
	s_waitcnt lgkmcnt(0)
	v_cmp_eq_u32_e32 vcc, v0, v218
	s_or_b64 s[14:15], vcc, s[14:15]
	s_andn2_b64 exec, exec, s[14:15]
	s_cbranch_execnz .LBB0_931
	s_or_b64 exec, exec, s[14:15]
	s_mulk_i32 s16, 0x4200
	v_add_u32_e32 v8, s16, v203
	ds_read2st64_b32 v[0:1], v8 offset1:32
	v_max_f32_e32 v4, v164, v164
	ds_read2st64_b32 v[2:3], v8 offset0:35 offset1:36
	v_cndmask_b32_e64 v17, v149, v109, s[12:13]
	s_waitcnt lgkmcnt(1)
	v_max_f32_e32 v5, v1, v1
	v_max_f32_e32 v4, v4, v5
	v_sub_f32_e32 v1, v1, v4
	v_sub_f32_e32 v5, v164, v4
	v_mul_f32_e32 v1, 0x3fb8aa3b, v1
	v_mul_f32_e32 v4, 0x3fb8aa3b, v5
	v_exp_f32_e32 v1, v1
	v_exp_f32_e32 v9, v4
	ds_read2st64_b32 v[4:5], v8 offset0:37 offset1:38
	ds_read_b32 v10, v8 offset:9984
	ds_read2st64_b32 v[6:7], v8 offset0:33 offset1:34
	s_waitcnt lgkmcnt(3)
	v_mul_f32_e32 v3, v3, v1
	v_fmac_f32_e32 v3, v191, v9
	v_div_scale_f32 v11, s[14:15], v3, v3, 1.0
	v_rcp_f32_e32 v12, v11
	s_nop 0
	v_fma_f32 v13, -v11, v12, 1.0
	v_fmac_f32_e32 v12, v13, v12
	v_div_scale_f32 v13, vcc, 1.0, v3, 1.0
	v_mul_f32_e32 v14, v13, v12
	v_fma_f32 v15, -v11, v14, v13
	v_fmac_f32_e32 v14, v15, v12
	v_fma_f32 v11, -v11, v14, v13
	s_waitcnt lgkmcnt(0)
	v_max_f32_e32 v13, v6, v6
	v_max_f32_e32 v15, v233, v233
	v_max_f32_e32 v13, v15, v13
	v_sub_f32_e32 v6, v6, v13
	v_sub_f32_e32 v15, v233, v13
	v_mul_f32_e32 v6, 0x3fb8aa3b, v6
	v_mul_f32_e32 v15, 0x3fb8aa3b, v15
	v_exp_f32_e32 v6, v6
	v_exp_f32_e32 v13, v15
	v_div_fmas_f32 v11, v11, v12, v14
	v_div_fixup_f32 v3, v11, v3, 1.0
	v_mul_f32_e32 v4, v4, v6
	v_fmac_f32_e32 v4, v190, v13
	v_div_scale_f32 v12, s[14:15], v4, v4, 1.0
	v_rcp_f32_e32 v14, v12
	v_mul_f32_e32 v9, v9, v3
	v_mul_f32_e32 v3, v1, v3
	v_mul_f32_e32 v0, v0, v3
	v_fma_f32 v1, -v12, v14, 1.0
	v_fmac_f32_e32 v14, v1, v14
	v_div_scale_f32 v1, vcc, 1.0, v4, 1.0
	v_mul_f32_e32 v11, v1, v14
	v_fma_f32 v15, -v12, v11, v1
	v_fmac_f32_e32 v11, v15, v14
	v_fma_f32 v1, -v12, v11, v1
	v_max_f32_e32 v12, v7, v7
	v_max_f32_e32 v15, v234, v234
	v_max_f32_e32 v12, v15, v12
	v_sub_f32_e32 v7, v7, v12
	v_sub_f32_e32 v15, v234, v12
	v_mul_f32_e32 v7, 0x3fb8aa3b, v7
	v_mul_f32_e32 v15, 0x3fb8aa3b, v15
	v_exp_f32_e32 v7, v7
	v_exp_f32_e32 v12, v15
	v_div_fmas_f32 v1, v1, v14, v11
	v_div_fixup_f32 v1, v1, v4, 1.0
	v_mul_f32_e32 v5, v5, v7
	v_fmac_f32_e32 v5, v187, v12
	v_div_scale_f32 v11, s[14:15], v5, v5, 1.0
	v_rcp_f32_e32 v14, v11
	v_mul_f32_e32 v4, v13, v1
	v_mul_f32_e32 v6, v6, v1
	v_fma_f32 v1, -v11, v14, 1.0
	v_fmac_f32_e32 v14, v1, v14
	v_div_scale_f32 v1, vcc, 1.0, v5, 1.0
	v_mul_f32_e32 v13, v1, v14
	v_fma_f32 v15, -v11, v13, v1
	v_fmac_f32_e32 v13, v15, v14
	v_fma_f32 v1, -v11, v13, v1
	v_max_f32_e32 v11, v2, v2
	v_max_f32_e32 v15, v235, v235
	v_max_f32_e32 v11, v15, v11
	v_sub_f32_e32 v2, v2, v11
	v_sub_f32_e32 v15, v235, v11
	v_mul_f32_e32 v2, 0x3fb8aa3b, v2
	v_mul_f32_e32 v15, 0x3fb8aa3b, v15
	v_exp_f32_e32 v2, v2
	v_exp_f32_e32 v11, v15
	v_div_fmas_f32 v1, v1, v14, v13
	v_div_fixup_f32 v1, v1, v5, 1.0
	v_mul_f32_e32 v10, v10, v2
	v_fmac_f32_e32 v10, v186, v11
	v_div_scale_f32 v13, s[14:15], v10, v10, 1.0
	v_rcp_f32_e32 v14, v13
	v_mul_f32_e32 v5, v12, v1
	v_mul_f32_e32 v7, v7, v1
	v_fma_f32 v1, -v13, v14, 1.0
	v_fmac_f32_e32 v14, v1, v14
	v_div_scale_f32 v1, vcc, 1.0, v10, 1.0
	v_mul_f32_e32 v12, v1, v14
	v_fma_f32 v15, -v13, v12, v1
	v_fmac_f32_e32 v12, v15, v14
	v_cndmask_b32_e64 v15, v148, v108, s[12:13]
	v_fmac_f32_e32 v0, v15, v9
	v_cvt_pk_bf16_f32 v15, v0, v165
	ds_read_b32 v16, v8 offset:256
	v_fma_f32 v13, -v13, v12, v1
	v_or_b32_e32 v1, v181, v204
	v_lshlrev_b32_e32 v164, 1, v1
	v_lshl_add_u64 v[0:1], v[184:185], 0, v[164:165]
	global_store_short v[0:1], v15, off nt
	s_waitcnt lgkmcnt(0)
	v_mul_f32_e32 v15, v6, v16
	v_fmac_f32_e32 v15, v17, v4
	v_cvt_pk_bf16_f32 v15, v15, v165
	ds_read_b32 v16, v8 offset:512
	v_div_fmas_f32 v12, v13, v14, v12
	v_div_fixup_f32 v10, v12, v10, 1.0
	v_cndmask_b32_e64 v12, v150, v110, s[12:13]
	global_store_short v[0:1], v15, off offset:512 nt
	s_waitcnt lgkmcnt(0)
	v_mul_f32_e32 v13, v7, v16
	v_fmac_f32_e32 v13, v12, v5
	v_cvt_pk_bf16_f32 v12, v13, v165
	ds_read_b32 v13, v8 offset:768
	v_mul_f32_e32 v2, v2, v10
	v_mul_f32_e32 v11, v11, v10
	v_cndmask_b32_e64 v10, v151, v111, s[12:13]
	global_store_short v[0:1], v12, off offset:1024 nt
	s_waitcnt lgkmcnt(0)
	v_mul_f32_e32 v12, v2, v13
	v_fmac_f32_e32 v12, v10, v11
	v_cvt_pk_bf16_f32 v10, v12, v165
	ds_read_b32 v12, v8 offset:1024
	global_store_short v[0:1], v10, off offset:1536 nt
	v_cndmask_b32_e64 v10, v136, v100, s[12:13]
	v_cndmask_b32_e64 v13, v137, v101, s[12:13]
	s_waitcnt lgkmcnt(0)
	v_mul_f32_e32 v12, v3, v12
	v_fmac_f32_e32 v12, v10, v9
	v_cvt_pk_bf16_f32 v10, v12, v165
	ds_read_b32 v12, v8 offset:1280
	global_store_short v[0:1], v10, off offset:32 nt
	s_waitcnt lgkmcnt(0)
	v_mul_f32_e32 v10, v6, v12
	v_fmac_f32_e32 v10, v13, v4
	v_cvt_pk_bf16_f32 v10, v10, v165
	ds_read_b32 v12, v8 offset:1536
	v_cndmask_b32_e64 v13, v138, v102, s[12:13]
	global_store_short v[0:1], v10, off offset:544 nt
	s_waitcnt lgkmcnt(0)
	v_mul_f32_e32 v10, v7, v12
	v_fmac_f32_e32 v10, v13, v5
	v_cvt_pk_bf16_f32 v10, v10, v165
	ds_read_b32 v12, v8 offset:1792
	v_cndmask_b32_e64 v13, v139, v103, s[12:13]
	global_store_short v[0:1], v10, off offset:1056 nt
	s_waitcnt lgkmcnt(0)
	v_mul_f32_e32 v10, v2, v12
	v_fmac_f32_e32 v10, v13, v11
	v_cvt_pk_bf16_f32 v10, v10, v165
	ds_read_b32 v12, v8 offset:2048
	global_store_short v[0:1], v10, off offset:1568 nt
	v_cndmask_b32_e64 v10, v124, v84, s[12:13]
	v_cndmask_b32_e64 v13, v125, v85, s[12:13]
	s_waitcnt lgkmcnt(0)
; __device__ __forceinline__ unsigned cvt_pk_bf16(float lo, float hi) { unsigned r; asm volatile("v_cvt_pk_bf16_f32 %0, %1, %2" : "=v"(r) : "v"(lo), "v"(hi)); return r; }
; __device__ __forceinline__ void attn_item(const Ptrs& P, unsigned char* lds, int b, int tq0, int tid) {
;     ...
;         for (int dt = 0; dt < 8; ++dt)
; #pragma unroll
;             for (int j = 0; j < 4; ++j) { const float v = (half ? oacc[8 + dt][j] : oacc[dt][j]) * wa[j] + pc[(dt * 4 + j) * 64 + lane] * wb[j];
;                 op[(4 * g + j) * 256 + 16 * (8 * half + dt) + r16] = (bf16_t)(cvt_pk_bf16(v, 0.f) & 0xffffu); }
	v_mul_f32_e32 v12, v3, v12
	v_fmac_f32_e32 v12, v10, v9
	v_cvt_pk_bf16_f32 v10, v12, v165
	ds_read_b32 v12, v8 offset:2304
	global_store_short v[0:1], v10, off offset:64 nt
	s_waitcnt lgkmcnt(0)
	v_mul_f32_e32 v10, v6, v12
	v_fmac_f32_e32 v10, v13, v4
	v_cvt_pk_bf16_f32 v10, v10, v165
	ds_read_b32 v12, v8 offset:2560
	v_cndmask_b32_e64 v13, v126, v86, s[12:13]
	global_store_short v[0:1], v10, off offset:576 nt
	s_waitcnt lgkmcnt(0)
	v_mul_f32_e32 v10, v7, v12
	v_fmac_f32_e32 v10, v13, v5
	v_cvt_pk_bf16_f32 v10, v10, v165
	ds_read_b32 v12, v8 offset:2816
	v_cndmask_b32_e64 v13, v127, v87, s[12:13]
	global_store_short v[0:1], v10, off offset:1088 nt
	s_waitcnt lgkmcnt(0)
	v_mul_f32_e32 v10, v2, v12
	v_fmac_f32_e32 v10, v13, v11
	v_cvt_pk_bf16_f32 v10, v10, v165
	ds_read_b32 v12, v8 offset:3072
	global_store_short v[0:1], v10, off offset:1600 nt
	v_cndmask_b32_e64 v10, v112, v68, s[12:13]
	v_cndmask_b32_e64 v13, v113, v69, s[12:13]
	s_waitcnt lgkmcnt(0)
	v_mul_f32_e32 v12, v3, v12
	v_fmac_f32_e32 v12, v10, v9
	v_cvt_pk_bf16_f32 v10, v12, v165
	ds_read_b32 v12, v8 offset:3328
	global_store_short v[0:1], v10, off offset:96 nt
	s_waitcnt lgkmcnt(0)
	v_mul_f32_e32 v10, v6, v12
	v_fmac_f32_e32 v10, v13, v4
	v_cvt_pk_bf16_f32 v10, v10, v165
	ds_read_b32 v12, v8 offset:3584
	v_cndmask_b32_e64 v13, v114, v70, s[12:13]
	global_store_short v[0:1], v10, off offset:608 nt
	s_waitcnt lgkmcnt(0)
	v_mul_f32_e32 v10, v7, v12
	v_fmac_f32_e32 v10, v13, v5
	v_cvt_pk_bf16_f32 v10, v10, v165
	ds_read_b32 v12, v8 offset:3840
	v_cndmask_b32_e64 v13, v115, v71, s[12:13]
	global_store_short v[0:1], v10, off offset:1120 nt
	s_waitcnt lgkmcnt(0)
	v_mul_f32_e32 v10, v2, v12
	v_fmac_f32_e32 v10, v13, v11
	v_cvt_pk_bf16_f32 v10, v10, v165
	ds_read_b32 v12, v8 offset:4096
	global_store_short v[0:1], v10, off offset:1632 nt
	v_cndmask_b32_e64 v10, v104, v48, s[12:13]
	v_cndmask_b32_e64 v13, v105, v49, s[12:13]
	s_waitcnt lgkmcnt(0)
	v_mul_f32_e32 v12, v3, v12
	v_fmac_f32_e32 v12, v10, v9
	v_cvt_pk_bf16_f32 v10, v12, v165
	ds_read_b32 v12, v8 offset:4352
	global_store_short v[0:1], v10, off offset:128 nt
	s_waitcnt lgkmcnt(0)
	v_mul_f32_e32 v10, v6, v12
	v_fmac_f32_e32 v10, v13, v4
	v_cvt_pk_bf16_f32 v10, v10, v165
	ds_read_b32 v12, v8 offset:4608
	v_cndmask_b32_e64 v13, v106, v50, s[12:13]
	global_store_short v[0:1], v10, off offset:640 nt
	s_waitcnt lgkmcnt(0)
	v_mul_f32_e32 v10, v7, v12
	v_fmac_f32_e32 v10, v13, v5
	v_cvt_pk_bf16_f32 v10, v10, v165
	ds_read_b32 v12, v8 offset:4864
	v_cndmask_b32_e64 v13, v107, v51, s[12:13]
	global_store_short v[0:1], v10, off offset:1152 nt
	s_waitcnt lgkmcnt(0)
	v_mul_f32_e32 v10, v2, v12
	v_fmac_f32_e32 v10, v13, v11
	v_cvt_pk_bf16_f32 v10, v10, v165
	ds_read_b32 v12, v8 offset:5120
	global_store_short v[0:1], v10, off offset:1664 nt
	v_cndmask_b32_e64 v10, v96, v40, s[12:13]
	v_cndmask_b32_e64 v13, v97, v41, s[12:13]
	s_waitcnt lgkmcnt(0)
	v_mul_f32_e32 v12, v3, v12
	v_fmac_f32_e32 v12, v10, v9
	v_cvt_pk_bf16_f32 v10, v12, v165
	ds_read_b32 v12, v8 offset:5376
	global_store_short v[0:1], v10, off offset:160 nt
	s_waitcnt lgkmcnt(0)
	v_mul_f32_e32 v10, v6, v12
	v_fmac_f32_e32 v10, v13, v4
	v_cvt_pk_bf16_f32 v10, v10, v165
	ds_read_b32 v12, v8 offset:5632
	v_cndmask_b32_e64 v13, v98, v42, s[12:13]
	global_store_short v[0:1], v10, off offset:672 nt
	s_waitcnt lgkmcnt(0)
	v_mul_f32_e32 v10, v7, v12
	v_fmac_f32_e32 v10, v13, v5
	v_cvt_pk_bf16_f32 v10, v10, v165
	ds_read_b32 v12, v8 offset:5888
	v_cndmask_b32_e64 v13, v99, v43, s[12:13]
	global_store_short v[0:1], v10, off offset:1184 nt
	s_waitcnt lgkmcnt(0)
	v_mul_f32_e32 v10, v2, v12
	v_fmac_f32_e32 v10, v13, v11
	v_cvt_pk_bf16_f32 v10, v10, v165
	ds_read_b32 v12, v8 offset:6144
	global_store_short v[0:1], v10, off offset:1696 nt
	v_cndmask_b32_e64 v10, v80, v36, s[12:13]
	v_cndmask_b32_e64 v13, v81, v37, s[12:13]
	s_waitcnt lgkmcnt(0)
	v_mul_f32_e32 v12, v3, v12
	v_fmac_f32_e32 v12, v10, v9
	v_cvt_pk_bf16_f32 v10, v12, v165
	ds_read_b32 v12, v8 offset:6400
	global_store_short v[0:1], v10, off offset:192 nt
	s_waitcnt lgkmcnt(0)
	v_mul_f32_e32 v10, v6, v12
	v_fmac_f32_e32 v10, v13, v4
	v_cvt_pk_bf16_f32 v10, v10, v165
	ds_read_b32 v12, v8 offset:6656
	v_cndmask_b32_e64 v13, v82, v38, s[12:13]
	global_store_short v[0:1], v10, off offset:704 nt
	s_waitcnt lgkmcnt(0)
	v_mul_f32_e32 v10, v7, v12
	v_fmac_f32_e32 v10, v13, v5
	v_cvt_pk_bf16_f32 v10, v10, v165
	ds_read_b32 v12, v8 offset:6912
	v_cndmask_b32_e64 v13, v83, v39, s[12:13]
	global_store_short v[0:1], v10, off offset:1216 nt
	s_waitcnt lgkmcnt(0)
	v_mul_f32_e32 v10, v2, v12
	v_fmac_f32_e32 v10, v13, v11
	v_cvt_pk_bf16_f32 v10, v10, v165
	ds_read_b32 v12, v8 offset:7168
	global_store_short v[0:1], v10, off offset:1728 nt
	v_cndmask_b32_e64 v10, v44, v32, s[12:13]
	s_waitcnt lgkmcnt(0)
	v_mul_f32_e32 v3, v3, v12
	v_fmac_f32_e32 v3, v10, v9
	v_cvt_pk_bf16_f32 v3, v3, v165
	ds_read_b32 v9, v8 offset:7424
	v_cndmask_b32_e64 v10, v45, v33, s[12:13]
	global_store_short v[0:1], v3, off offset:224 nt
	s_waitcnt lgkmcnt(0)
	v_mul_f32_e32 v3, v6, v9
	v_fmac_f32_e32 v3, v10, v4
	v_cvt_pk_bf16_f32 v3, v3, v165
	ds_read_b32 v4, v8 offset:7680
	v_cndmask_b32_e64 v6, v46, v34, s[12:13]
	global_store_short v[0:1], v3, off offset:736 nt
	s_waitcnt lgkmcnt(0)
	v_mul_f32_e32 v3, v7, v4
	v_fmac_f32_e32 v3, v6, v5
	v_cvt_pk_bf16_f32 v3, v3, v165
	ds_read_b32 v4, v8 offset:7936
	v_cndmask_b32_e64 v5, v47, v35, s[12:13]
	s_xor_b64 s[12:13], exec, -1
	global_store_short v[0:1], v3, off offset:1248 nt
	s_waitcnt lgkmcnt(0)
	v_mul_f32_e32 v2, v2, v4
	v_fmac_f32_e32 v2, v5, v11
	v_cvt_pk_bf16_f32 v2, v2, v165
	global_store_short v[0:1], v2, off offset:1760 nt
	s_branch .Lq_next
